# SSD MFMA operand reads issued two MFMAs ahead (without the attention change)
# speedup vs baseline: 1.0372x; 1.0021x over previous
.LBB0_2428:
	s_lshl_b32 s38, s61, 7
	s_add_u32 s38, s58, s38
	s_addc_u32 s39, s59, 0
	v_or_b32_e32 v102, s38, v101
	v_mov_b32_e32 v103, s39
	v_lshlrev_b64 v[102:103], 13, v[102:103]
	v_lshlrev_b32_e32 v100, 2, v100
	v_lshl_add_u64 v[102:103], s[34:35], 0, v[102:103]
	v_ashrrev_i32_e32 v101, 31, v100
	v_lshl_add_u64 v[108:109], v[100:101], 2, v[102:103]
	v_mul_lo_u32 v99, v99, s53
	v_add_lshl_u32 v100, v100, s40, 1
	v_add3_u32 v99, 0, v99, v100
	ds_read2_b64 v[100:103], v99 offset1:2
	ds_read2_b64 v[104:107], v99 offset0:4 offset1:6
	s_waitcnt lgkmcnt(1)
	v_lshlrev_b32_e32 v110, 16, v100
	v_and_b32_e32 v111, 0xffff0000, v100
	v_lshlrev_b32_e32 v100, 16, v101
	v_and_b32_e32 v101, 0xffff0000, v101
	v_pk_fma_f32 v[18:19], v[82:83], v[110:111], v[18:19]
	v_pk_fma_f32 v[20:21], v[82:83], v[100:101], v[20:21]
	global_store_dwordx4 v[108:109], v[18:21], off
	s_nop 1
	v_lshlrev_b32_e32 v18, 16, v102
	v_and_b32_e32 v19, 0xffff0000, v102
	v_lshlrev_b32_e32 v20, 16, v103
	v_and_b32_e32 v21, 0xffff0000, v103
	v_pk_fma_f32 v[18:19], v[82:83], v[18:19], v[22:23]
	v_pk_fma_f32 v[20:21], v[82:83], v[20:21], v[24:25]
	global_store_dwordx4 v[108:109], v[18:21], off offset:32
	s_waitcnt lgkmcnt(0)
	s_nop 0
	v_lshlrev_b32_e32 v18, 16, v104
	v_and_b32_e32 v19, 0xffff0000, v104
	v_lshlrev_b32_e32 v20, 16, v105
	v_and_b32_e32 v21, 0xffff0000, v105
	v_pk_fma_f32 v[18:19], v[82:83], v[18:19], v[26:27]
	v_pk_fma_f32 v[20:21], v[82:83], v[20:21], v[28:29]
	global_store_dwordx4 v[108:109], v[18:21], off offset:64
	s_nop 1
	v_lshlrev_b32_e32 v18, 16, v106
	v_and_b32_e32 v19, 0xffff0000, v106
	v_lshlrev_b32_e32 v20, 16, v107
	v_and_b32_e32 v21, 0xffff0000, v107
	v_pk_fma_f32 v[18:19], v[82:83], v[18:19], v[30:31]
	v_pk_fma_f32 v[20:21], v[82:83], v[20:21], v[32:33]
	global_store_dwordx4 v[108:109], v[18:21], off offset:96
	s_nop 1
	v_mov_b32_e32 v18, s56
	ds_read_b32 v18, v18
	s_waitcnt lgkmcnt(0)
	v_mul_f32_e32 v18, 0x3fb8aa3b, v18
	v_exp_f32_e32 v18, v18
	s_nop 0
	v_pk_mul_f32 v[16:17], v[16:17], v[18:19] op_sel_hi:[1,0]
	v_pk_mul_f32 v[14:15], v[14:15], v[18:19] op_sel_hi:[1,0]
	v_pk_mul_f32 v[12:13], v[12:13], v[18:19] op_sel_hi:[1,0]
	v_pk_mul_f32 v[10:11], v[10:11], v[18:19] op_sel_hi:[1,0]
	v_pk_mul_f32 v[8:9], v[8:9], v[18:19] op_sel_hi:[1,0]
	v_pk_mul_f32 v[6:7], v[6:7], v[18:19] op_sel_hi:[1,0]
	v_pk_mul_f32 v[4:5], v[4:5], v[18:19] op_sel_hi:[1,0]
	v_pk_mul_f32 v[2:3], v[2:3], v[18:19] op_sel_hi:[1,0]
	v_mul_lo_u32 v19, v74, s55
	v_add3_u32 v30, 0, v98, v19
	ds_read_b64_tr_b16 v[120:121], v30 offset:36864
	ds_read_b64_tr_b16 v[122:123], v30 offset:37952
	v_add_u32_e32 v18, 0, v97
	v_or_b32_e32 v19, 4, v74
	v_add_u32_e32 v31, v18, v96
	v_mad_u64_u32 v[26:27], s[38:39], v19, s53, v[18:19]
	ds_read_b64_tr_b16 v[124:125], v31 offset:18432
	ds_read_b64_tr_b16 v[126:127], v26 offset:18432
	v_mad_u64_u32 v[28:29], s[38:39], v74, s53, v[18:19]
	ds_read_b64_tr_b16 v[128:129], v30 offset:41216
	ds_read_b64_tr_b16 v[130:131], v30 offset:42304
	ds_read_b64_tr_b16 v[132:133], v31 offset:20736
	ds_read_b64_tr_b16 v[134:135], v28 offset:21312
	ds_read_b64_tr_b16 v[136:137], v30 offset:45568
	ds_read_b64_tr_b16 v[138:139], v30 offset:46656
	ds_read_b64_tr_b16 v[140:141], v31 offset:23040
	ds_read_b64_tr_b16 v[142:143], v28 offset:23616
	s_waitcnt lgkmcnt(8)
	v_mfma_f32_32x32x16_bf16 v[2:17], v[120:123], v[124:127], v[2:17]
	ds_read_b64_tr_b16 v[144:145], v30 offset:49920
	ds_read_b64_tr_b16 v[146:147], v30 offset:51008
	ds_read_b64_tr_b16 v[148:149], v31 offset:25344
	ds_read_b64_tr_b16 v[150:151], v28 offset:25920
	s_waitcnt lgkmcnt(8)
	v_mfma_f32_32x32x16_bf16 v[2:17], v[128:131], v[132:135], v[2:17]
	ds_read_b64_tr_b16 v[120:121], v30 offset:54272
	ds_read_b64_tr_b16 v[122:123], v30 offset:55360
	ds_read_b64_tr_b16 v[124:125], v31 offset:27648
	ds_read_b64_tr_b16 v[126:127], v28 offset:28224
	s_waitcnt lgkmcnt(8)
	v_mfma_f32_32x32x16_bf16 v[2:17], v[136:139], v[140:143], v[2:17]
	v_add_u32_e32 v29, v18, v81
	ds_read_b64_tr_b16 v[128:129], v30 offset:58624
	ds_read_b64_tr_b16 v[130:131], v30 offset:59712
	ds_read_b64_tr_b16 v[132:133], v29 offset:18432
	ds_read_b64_tr_b16 v[134:135], v28 offset:30528
	s_waitcnt lgkmcnt(8)
	v_mfma_f32_32x32x16_bf16 v[2:17], v[144:147], v[148:151], v[2:17]
	ds_read_b64_tr_b16 v[136:137], v30 offset:62976
	ds_read_b64_tr_b16 v[138:139], v30 offset:64064
	ds_read_b64_tr_b16 v[140:141], v29 offset:20736
	ds_read_b64_tr_b16 v[142:143], v28 offset:32832
	s_waitcnt lgkmcnt(8)
	v_mfma_f32_32x32x16_bf16 v[2:17], v[120:123], v[124:127], v[2:17]
	v_add_u32_e32 v18, 0x10700, v30
	ds_read_b64_tr_b16 v[144:145], v18
	v_add_u32_e32 v20, 0x10b40, v30
	ds_read_b64_tr_b16 v[146:147], v20
	ds_read_b64_tr_b16 v[148:149], v29 offset:23040
	ds_read_b64_tr_b16 v[150:151], v28 offset:35136
	s_waitcnt lgkmcnt(8)
	v_mfma_f32_32x32x16_bf16 v[2:17], v[128:131], v[132:135], v[2:17]
	s_waitcnt lgkmcnt(4)
	v_mfma_f32_32x32x16_bf16 v[2:17], v[136:139], v[140:143], v[2:17]
	s_waitcnt lgkmcnt(0)
	v_mfma_f32_32x32x16_bf16 v[2:17], v[144:147], v[148:151], v[2:17]
	s_cmp_eq_u32 s60, 16
	s_mov_b32 s61, s60
	s_waitcnt vmcnt(15)
	v_mov_b32_e32 v22, v66
	v_mov_b32_e32 v23, v67
	v_mov_b32_e32 v24, v68
	v_mov_b32_e32 v25, v69
	s_waitcnt vmcnt(14)
	v_mov_b32_e32 v18, v70
	v_mov_b32_e32 v19, v71
	v_mov_b32_e32 v20, v72
	v_mov_b32_e32 v21, v73
	s_barrier
	s_cbranch_scc1 .LBB0_2426

.LBB0_2435:
	s_cmp_lt_u32 s38, 6
	s_cselect_b32 s39, 2, 3
	s_cmp_gt_u32 s38, 2
	s_cselect_b32 s39, s39, 1
	s_cmp_gt_i32 s38, 0
	s_cselect_b32 s39, s39, 0
	s_add_i32 s62, s39, 1
	s_mul_i32 s62, s62, s39
	s_lshr_b32 s62, s62, 1
	s_mul_i32 s63, s62, 0xffffde00
	s_add_i32 s63, s63, 0
	v_lshl_or_b32 v110, s39, 5, v74
	v_add_u32_e32 v111, s63, v98
	v_mad_u32_u24 v112, v110, s55, v97
	ds_read_b128 v[120:123], v111
	ds_read_b128 v[128:131], v111 offset:32
	ds_read_b128 v[124:127], v112
	ds_read_b128 v[132:135], v112 offset:32
	s_lshl_b32 s63, s62, 5
	s_lshl_b32 s39, s39, 6
	v_add_u32_e32 v98, 0x11000, v98
	ds_read_b128 v[136:139], v111 offset:64
	ds_read_b128 v[140:143], v112 offset:64
	s_waitcnt lgkmcnt(3)
	v_mfma_f32_32x32x16_bf16 v[18:33], v[120:123], v[124:127], 0
	ds_read_b128 v[144:147], v111 offset:96
	ds_read_b128 v[148:151], v112 offset:96
	s_waitcnt lgkmcnt(4)
	v_mfma_f32_32x32x16_bf16 v[18:33], v[128:131], v[132:135], v[18:33]
	ds_read_b128 v[120:123], v111 offset:128
	ds_read_b128 v[124:127], v112 offset:128
	s_waitcnt lgkmcnt(4)
	v_mfma_f32_32x32x16_bf16 v[18:33], v[136:139], v[140:143], v[18:33]
	ds_read_b128 v[128:131], v111 offset:160
	ds_read_b128 v[132:135], v112 offset:160
	s_waitcnt lgkmcnt(4)
	v_mfma_f32_32x32x16_bf16 v[18:33], v[144:147], v[148:151], v[18:33]
	ds_read_b128 v[136:139], v111 offset:192
	ds_read_b128 v[140:143], v112 offset:192
	s_waitcnt lgkmcnt(4)
	v_mfma_f32_32x32x16_bf16 v[18:33], v[120:123], v[124:127], v[18:33]
	ds_read_b128 v[144:147], v111 offset:224
	ds_read_b128 v[148:151], v112 offset:224
	s_waitcnt lgkmcnt(4)
	v_mfma_f32_32x32x16_bf16 v[18:33], v[128:131], v[132:135], v[18:33]
	s_waitcnt lgkmcnt(2)
	v_mfma_f32_32x32x16_bf16 v[18:33], v[136:139], v[140:143], v[18:33]
	s_waitcnt lgkmcnt(0)
	v_mfma_f32_32x32x16_bf16 v[18:33], v[144:147], v[148:151], v[18:33]
	v_subrev_u32_e32 v112, s63, v100
	s_lshl_b32 s63, s62, 7
	s_sub_i32 s63, 0, s63
	v_add_u32_e32 v114, s63, v99
	s_mulk_i32 s62, 0x2200
	v_subrev_u32_e32 v113, 27, v112
	v_lshl_add_u32 v102, v110, 2, 0
	v_add_u32_e32 v102, 0x27000, v102
	v_add_u32_e32 v106, 0x27200, v114
	ds_read_b32 v111, v102
	ds_read_b128 v[106:109], v106
	v_add_u32_e32 v102, 0x27000, v114
	ds_read_b128 v[102:105], v102
	s_sub_i32 s39, s39, s62
	v_cmp_le_i32_e32 vcc, v113, v110
	s_add_i32 s39, s39, 0
	v_add_u32_e32 v99, 0x400, v99
	s_waitcnt lgkmcnt(0)
	v_sub_f32_e32 v102, v111, v102
	v_mul_f32_e32 v102, 0x3fb8aa3b, v102
	v_exp_f32_e32 v102, v102
	v_add_u32_e32 v100, 0x100, v100
	v_mul_f32_e32 v18, v18, v102
	v_mul_f32_e32 v18, v106, v18
	v_cndmask_b32_e32 v18, 0, v18, vcc
	v_add_u32_e32 v106, s39, v101
	v_cvt_pk_bf16_f32 v18, v18, v75
	v_add_u32_e32 v102, 0x1a000, v106
	ds_write_b16 v102, v18
	v_sub_f32_e32 v18, v111, v103
	v_mul_f32_e32 v18, 0x3fb8aa3b, v18
	v_exp_f32_e32 v18, v18
	v_cmp_lt_i32_e32 vcc, v113, v110
	v_add_u32_e32 v102, 0x27220, v114
	s_add_i32 s39, s38, 8
	v_mul_f32_e32 v18, v19, v18
	v_mul_f32_e32 v18, v107, v18
	v_cndmask_b32_e32 v18, 0, v18, vcc
	v_add_u32_e32 v19, 0x1a110, v106
	v_cvt_pk_bf16_f32 v18, v18, v75
	ds_write_b16 v19, v18
	v_sub_f32_e32 v19, v111, v104
	v_mul_f32_e32 v19, 0x3fb8aa3b, v19
	v_exp_f32_e32 v19, v19
	v_subrev_u32_e32 v18, 25, v112
	v_cmp_le_i32_e32 vcc, v18, v110
	v_subrev_u32_e32 v107, 19, v112
	v_mul_f32_e32 v19, v20, v19
	v_mul_f32_e32 v19, v108, v19
	v_cndmask_b32_e32 v18, 0, v19, vcc
	v_add_u32_e32 v19, 0x1a220, v106
	v_cvt_pk_bf16_f32 v18, v18, v75
	ds_write_b16 v19, v18
	v_sub_f32_e32 v19, v111, v105
	v_mul_f32_e32 v19, 0x3fb8aa3b, v19
	v_exp_f32_e32 v19, v19
	v_subrev_u32_e32 v18, 24, v112
	v_cmp_le_i32_e32 vcc, v18, v110
	v_add_u32_e32 v101, 0x11000, v101
	v_mul_f32_e32 v19, v21, v19
	v_mul_f32_e32 v19, v109, v19
	v_cndmask_b32_e32 v18, 0, v19, vcc
	v_cvt_pk_bf16_f32 v18, v18, v75
	v_add_u32_e32 v19, 0x1a330, v106
	ds_write_b16 v19, v18
	v_add_u32_e32 v18, 0x27020, v114
	ds_read_b128 v[18:21], v18
	ds_read_b128 v[102:105], v102
	v_cmp_le_i32_e32 vcc, v107, v110
	s_cmp_gt_i32 s38, 1
	s_mov_b32 s38, s39
	s_waitcnt lgkmcnt(1)
	v_sub_f32_e32 v18, v111, v18
	v_mul_f32_e32 v18, 0x3fb8aa3b, v18
	v_exp_f32_e32 v18, v18
	s_nop 0
	v_mul_f32_e32 v18, v22, v18
	s_waitcnt lgkmcnt(0)
	v_mul_f32_e32 v18, v102, v18
	v_cndmask_b32_e32 v18, 0, v18, vcc
	v_cvt_pk_bf16_f32 v18, v18, v75
	v_add_u32_e32 v22, 0x1a880, v106
	ds_write_b16 v22, v18
	v_sub_f32_e32 v18, v111, v19
	v_mul_f32_e32 v18, 0x3fb8aa3b, v18
	v_exp_f32_e32 v18, v18
	v_cmp_lt_i32_e32 vcc, v107, v110
	v_add_u32_e32 v19, 0x1a990, v106
	v_add_u32_e32 v22, 0x27240, v114
	v_mul_f32_e32 v18, v23, v18
	v_mul_f32_e32 v18, v103, v18
	v_cndmask_b32_e32 v18, 0, v18, vcc
	v_cvt_pk_bf16_f32 v18, v18, v75
	ds_write_b16 v19, v18
	v_sub_f32_e32 v19, v111, v20
	v_mul_f32_e32 v19, 0x3fb8aa3b, v19
	v_exp_f32_e32 v19, v19
	v_subrev_u32_e32 v18, 17, v112
	v_cmp_le_i32_e32 vcc, v18, v110
	v_add_u32_e32 v102, -11, v112
	v_mul_f32_e32 v19, v24, v19
	v_mul_f32_e32 v19, v104, v19
	v_cndmask_b32_e32 v18, 0, v19, vcc
	v_add_u32_e32 v19, 0x1aaa0, v106
	v_cvt_pk_bf16_f32 v18, v18, v75
	ds_write_b16 v19, v18
	v_sub_f32_e32 v19, v111, v21
	v_mul_f32_e32 v19, 0x3fb8aa3b, v19
	v_exp_f32_e32 v19, v19
	v_add_u32_e32 v18, -16, v112
	v_cmp_le_i32_e32 vcc, v18, v110
	v_mul_f32_e32 v19, v25, v19
	v_mul_f32_e32 v19, v105, v19
	v_cndmask_b32_e32 v18, 0, v19, vcc
	v_cvt_pk_bf16_f32 v18, v18, v75
	v_add_u32_e32 v19, 0x1abb0, v106
	ds_write_b16 v19, v18
	v_add_u32_e32 v18, 0x27040, v114
	ds_read_b128 v[18:21], v18
	ds_read_b128 v[22:25], v22
	v_cmp_le_i32_e32 vcc, v102, v110
	s_waitcnt lgkmcnt(1)
	v_sub_f32_e32 v18, v111, v18
	v_mul_f32_e32 v18, 0x3fb8aa3b, v18
	v_exp_f32_e32 v18, v18
	s_nop 0
	v_mul_f32_e32 v18, v26, v18
	s_waitcnt lgkmcnt(0)
	v_mul_f32_e32 v18, v22, v18
	v_cndmask_b32_e32 v18, 0, v18, vcc
	v_cvt_pk_bf16_f32 v18, v18, v75
	v_add_u32_e32 v22, 0x1b100, v106
	ds_write_b16 v22, v18
	v_sub_f32_e32 v18, v111, v19
	v_mul_f32_e32 v18, 0x3fb8aa3b, v18
	v_exp_f32_e32 v18, v18
	v_cmp_lt_i32_e32 vcc, v102, v110
	v_add_u32_e32 v19, 0x1b210, v106
	v_add_u32_e32 v22, 0x27260, v114
	v_mul_f32_e32 v18, v27, v18
	v_mul_f32_e32 v18, v23, v18
	v_cndmask_b32_e32 v18, 0, v18, vcc
	v_cvt_pk_bf16_f32 v18, v18, v75
	ds_write_b16 v19, v18
	v_sub_f32_e32 v19, v111, v20
	v_mul_f32_e32 v19, 0x3fb8aa3b, v19
	v_exp_f32_e32 v19, v19
	v_add_u32_e32 v18, -9, v112
	v_cmp_le_i32_e32 vcc, v18, v110
	v_add_u32_e32 v26, -3, v112
	v_mul_f32_e32 v19, v28, v19
	v_mul_f32_e32 v19, v24, v19
	v_cndmask_b32_e32 v18, 0, v19, vcc
	v_add_u32_e32 v19, 0x1b320, v106
	v_cvt_pk_bf16_f32 v18, v18, v75
	ds_write_b16 v19, v18
	v_sub_f32_e32 v19, v111, v21
	v_mul_f32_e32 v19, 0x3fb8aa3b, v19
	v_exp_f32_e32 v19, v19
	v_add_u32_e32 v18, -8, v112
	v_cmp_le_i32_e32 vcc, v18, v110
	v_mul_f32_e32 v19, v29, v19
	v_mul_f32_e32 v19, v25, v19
	v_cndmask_b32_e32 v18, 0, v19, vcc
	v_cvt_pk_bf16_f32 v18, v18, v75
	v_add_u32_e32 v19, 0x1b430, v106
	ds_write_b16 v19, v18
	v_add_u32_e32 v18, 0x27060, v114
	ds_read_b128 v[18:21], v18
	ds_read_b128 v[22:25], v22
	v_cmp_le_i32_e32 vcc, v26, v110
	s_waitcnt lgkmcnt(1)
	v_sub_f32_e32 v18, v111, v18
	v_mul_f32_e32 v18, 0x3fb8aa3b, v18
	v_exp_f32_e32 v18, v18
	s_nop 0
	v_mul_f32_e32 v18, v30, v18
	s_waitcnt lgkmcnt(0)
	v_mul_f32_e32 v18, v22, v18
	v_cndmask_b32_e32 v18, 0, v18, vcc
	v_cvt_pk_bf16_f32 v18, v18, v75
	v_add_u32_e32 v22, 0x1b980, v106
	ds_write_b16 v22, v18
	v_sub_f32_e32 v18, v111, v19
	v_mul_f32_e32 v18, 0x3fb8aa3b, v18
	v_exp_f32_e32 v18, v18
	v_cmp_lt_i32_e32 vcc, v26, v110
	v_add_u32_e32 v19, 0x1ba90, v106
	v_mul_f32_e32 v18, v31, v18
	v_mul_f32_e32 v18, v23, v18
	v_cndmask_b32_e32 v18, 0, v18, vcc
	v_cvt_pk_bf16_f32 v18, v18, v75
	ds_write_b16 v19, v18
	v_sub_f32_e32 v19, v111, v20
	v_mul_f32_e32 v19, 0x3fb8aa3b, v19
	v_exp_f32_e32 v19, v19
	v_add_u32_e32 v18, -1, v112
	v_cmp_le_i32_e32 vcc, v18, v110
	v_mul_f32_e32 v19, v32, v19
	v_mul_f32_e32 v19, v24, v19
	v_cndmask_b32_e32 v18, 0, v19, vcc
	v_cvt_pk_bf16_f32 v18, v18, v75
	v_add_u32_e32 v19, 0x1bba0, v106
	ds_write_b16 v19, v18
	v_sub_f32_e32 v18, v111, v21
	v_mul_f32_e32 v18, 0x3fb8aa3b, v18
	v_exp_f32_e32 v18, v18
	v_cmp_le_i32_e32 vcc, v112, v110
	v_add_u32_e32 v19, 0x1bcb0, v106
	v_mul_f32_e32 v18, v33, v18
	v_mul_f32_e32 v18, v25, v18
	v_cndmask_b32_e32 v18, 0, v18, vcc
	v_cvt_pk_bf16_f32 v18, v18, v75
	ds_write_b16 v19, v18
	s_cbranch_scc0 .LBB0_2435
	v_mov_b32_e32 v20, v81
	v_mov_b32_e32 v19, v96
.LBB0_2437:
	v_add_u32_e32 v18, s5, v20
	v_mul_lo_u32 v18, v18, s53
	v_add3_u32 v18, s33, v19, v18
	v_cvt_pk_bf16_f32 v20, v2, v75
	ds_write_b16 v18, v20
	v_cvt_pk_bf16_f32 v19, v3, v75
	ds_write_b16 v18, v19 offset:144
	v_cvt_pk_bf16_f32 v19, v4, v75
	ds_write_b16 v18, v19 offset:288
	v_cvt_pk_bf16_f32 v19, v5, v75
	ds_write_b16 v18, v19 offset:432
	v_cvt_pk_bf16_f32 v19, v6, v75
	ds_write_b16 v18, v19 offset:1152
	v_cvt_pk_bf16_f32 v19, v7, v75
	ds_write_b16 v18, v19 offset:1296
	v_cvt_pk_bf16_f32 v19, v8, v75
	ds_write_b16 v18, v19 offset:1440
	v_cvt_pk_bf16_f32 v19, v9, v75
	ds_write_b16 v18, v19 offset:1584
	v_cvt_pk_bf16_f32 v19, v10, v75
	ds_write_b16 v18, v19 offset:2304
	v_cvt_pk_bf16_f32 v19, v11, v75
	ds_write_b16 v18, v19 offset:2448
	v_cvt_pk_bf16_f32 v19, v12, v75
	ds_write_b16 v18, v19 offset:2592
	v_cvt_pk_bf16_f32 v19, v13, v75
	ds_write_b16 v18, v19 offset:2736
	v_cvt_pk_bf16_f32 v19, v14, v75
	ds_write_b16 v18, v19 offset:3456
	v_cvt_pk_bf16_f32 v19, v15, v75
	ds_write_b16 v18, v19 offset:3600
	v_cvt_pk_bf16_f32 v19, v16, v75
	ds_write_b16 v18, v19 offset:3744
	v_cvt_pk_bf16_f32 v19, v17, v75
	ds_write_b16 v18, v19 offset:3888
	v_mov_b32_e32 v18, v87
	s_waitcnt lgkmcnt(0)
	s_barrier
	s_add_i32 s38, 0, 0x22800
	v_and_b32_e32 v101, 31, v18
	v_ashrrev_i32_e32 v100, 5, v18
	v_ashrrev_i32_e32 v105, 2, v18
	v_bfe_u32 v102, v18, 2, 2
	v_and_b32_e32 v103, 16, v18
	v_lshlrev_b32_e32 v18, 2, v18
	v_and_b32_e32 v104, 12, v18
	v_or_b32_e32 v98, v104, v103
	v_or_b32_e32 v18, s40, v98
	v_and_or_b32 v74, v105, -8, v102
	v_lshlrev_b32_e32 v97, 1, v18
	v_add_u32_e32 v118, s38, v97
	v_mul_lo_u32 v96, v74, s53
	v_add_u32_e32 v18, v118, v96
	v_add3_u32 v20, s38, v96, v97
	ds_read_b64_tr_b16 v[120:121], v18
	ds_read_b64_tr_b16 v[122:123], v20 offset:576
	v_or_b32_e32 v99, s5, v101
	v_mul_lo_u32 v22, v99, s55
	v_lshlrev_b32_e32 v23, 4, v100
	v_add3_u32 v119, s54, v22, v23
	ds_read_b128 v[124:127], v119
	v_add_u32_e32 v81, 0x900, v96
	v_add_u32_e32 v106, v118, v81
	ds_read_b64_tr_b16 v[128:129], v106
	v_add3_u32 v81, s38, v81, v97
	ds_read_b64_tr_b16 v[130:131], v81 offset:576
	ds_read_b128 v[132:135], v119 offset:32
	v_add_u32_e32 v81, 0x1200, v96
	v_add_u32_e32 v106, v118, v81
	ds_read_b64_tr_b16 v[136:137], v106
	v_add3_u32 v81, s38, v81, v97
	ds_read_b64_tr_b16 v[138:139], v81 offset:576
	ds_read_b128 v[140:143], v119 offset:64
	s_waitcnt lgkmcnt(6)
	v_mfma_f32_32x32x16_bf16 v[18:33], v[120:123], v[124:127], 0
	ds_read_b128 v[148:151], v119 offset:96
	v_add_u32_e32 v81, 0x1b00, v96
	v_add_u32_e32 v106, v118, v81
	v_add3_u32 v81, s38, v81, v97
	ds_read_b64_tr_b16 v[144:145], v106
	ds_read_b64_tr_b16 v[146:147], v81 offset:576
	s_waitcnt lgkmcnt(6)
	v_mfma_f32_32x32x16_bf16 v[18:33], v[128:131], v[132:135], v[18:33]
	v_add_u32_e32 v81, 0x2400, v96
	v_add_u32_e32 v106, v118, v81
	ds_read_b64_tr_b16 v[120:121], v106
	v_add3_u32 v81, s38, v81, v97
	ds_read_b64_tr_b16 v[122:123], v81 offset:576
	ds_read_b128 v[124:127], v119 offset:128
	s_waitcnt lgkmcnt(6)
	v_mfma_f32_32x32x16_bf16 v[18:33], v[136:139], v[140:143], v[18:33]
	ds_read_b128 v[132:135], v119 offset:160
	v_add_u32_e32 v81, 0x2d00, v96
	v_add_u32_e32 v106, v118, v81
	v_add3_u32 v108, s38, v81, v97
	ds_read_b64_tr_b16 v[128:129], v106
	ds_read_b64_tr_b16 v[130:131], v108 offset:576
	s_waitcnt lgkmcnt(6)
	v_mfma_f32_32x32x16_bf16 v[18:33], v[144:147], v[148:151], v[18:33]
	v_add_u32_e32 v108, 0x3600, v96
	v_add_u32_e32 v106, v118, v108
	ds_read_b64_tr_b16 v[136:137], v106
	v_add3_u32 v108, s38, v108, v97
	ds_read_b64_tr_b16 v[138:139], v108 offset:576
	ds_read_b128 v[140:143], v119 offset:192
	s_waitcnt lgkmcnt(6)
	v_mfma_f32_32x32x16_bf16 v[18:33], v[120:123], v[124:127], v[18:33]
	v_add_u32_e32 v114, 0x3f00, v96
	v_add_u32_e32 v115, v118, v114
	v_add3_u32 v116, s38, v114, v97
	ds_read_b64_tr_b16 v[144:145], v115
	ds_read_b64_tr_b16 v[146:147], v116 offset:576
	ds_read_b128 v[148:151], v119 offset:224
	s_waitcnt lgkmcnt(6)
	v_mfma_f32_32x32x16_bf16 v[18:33], v[128:131], v[132:135], v[18:33]
	s_waitcnt lgkmcnt(3)
	v_mfma_f32_32x32x16_bf16 v[18:33], v[136:139], v[140:143], v[18:33]
	s_waitcnt lgkmcnt(0)
	v_mfma_f32_32x32x16_bf16 v[18:33], v[144:147], v[148:151], v[18:33]
	v_lshl_add_u32 v106, v99, 2, 0
	v_add_u32_e32 v106, 0x27000, v106
	ds_read_b32 v107, v106
	s_mov_b64 s[38:39], -1
	s_and_b64 vcc, exec, s[2:3]
	v_or_b32_e32 v106, s5, v98
	s_cbranch_vccz .LBB0_2439
	v_lshlrev_b32_e32 v98, 1, v106
	s_mov_b64 s[38:39], 0
